# attention epilogue: queue atomic and gate loads hoisted to start of final tile step
# speedup vs baseline: 1.0107x; 1.0042x over previous
; template<int THRL> __device__ __forceinline__ void attn_unit(int b,int h,int qb,int t0,float cqv,float mfix,const float*__restrict__ cf,float cref,unsigned*counter,const bf16*Q,const bf16*__restrict__ K,const bf16*__restrict__ V,bf16*O,const bf16*__restrict__ G,char*shm){
;     ...
;   int unext_=0; if(tid==0) unext_=(int)atomicAdd(counter,1u);
.LBB0_874:
	v_cmp_eq_u32_e64 s[100:101], 0, v226
	v_mov_b32_e32 v252, 1
	s_and_saveexec_b64 s[100:101], s[100:101]
	global_atomic_add v252, v205, v252, s[10:11] offset:256 sc0
	s_mov_b64 exec, s[100:101]
	s_lshl_b64 s[98:99], s[38:39], 1
	v_lshlrev_b32_e32 v196, 1, v225
	v_lshlrev_b32_e32 v197, 8, v224
	s_add_u32 s98, s2, s98
	s_addc_u32 s99, s3, s99
	v_and_b32_e32 v196, 0x70, v196
	v_and_b32_e32 v197, 0x3800, v197
	s_add_u32 s98, s98, s52
	s_addc_u32 s99, s99, s53
	v_add_u32_e32 v196, v196, v197
	v_add_u32_e32 v197, 0x4000, v196
	v_add_u32_e32 v198, 0x8000, v196
	v_add_u32_e32 v199, 0xc000, v196
	global_load_dwordx4 v[180:183], v196, s[98:99]
	global_load_dwordx4 v[184:187], v197, s[98:99]
	global_load_dwordx4 v[188:191], v198, s[98:99]
	global_load_dwordx4 v[192:195], v199, s[98:99]
	s_cmp_lg_u32 0, -1
	s_cselect_b32 s4, 0, 0
	s_addk_i32 s4, 0x6000
	v_add3_u32 v33, v234, s4, v232
	v_add_u32_e32 v38, s72, v235
	ds_read_b64_tr_b16 v[176:177], v38 offset:24576
	ds_read_b64_tr_b16 v[178:179], v38 offset:25088
	v_add_f32_e32 v34, v64, v65
	v_add_f32_e32 v34, v66, v34
	v_add_f32_e32 v34, v67, v34
	v_add_f32_e32 v34, v68, v34
	v_add_f32_e32 v34, v69, v34
	v_cvt_pk_bf16_f32 v128, v64, v65
	v_cvt_pk_bf16_f32 v129, v66, v67
	s_waitcnt lgkmcnt(3)
	v_mfma_f32_32x32x16_bf16 v[96:111], v[172:175], v[124:127], 0
	ds_read_b64_tr_b16 v[172:173], v38 offset:28672
	ds_read_b64_tr_b16 v[174:175], v38 offset:29184
	v_add_f32_e32 v34, v70, v34
	v_add_f32_e32 v34, v71, v34
	v_add_f32_e32 v34, v72, v34
	v_add_f32_e32 v39, v73, v34
	v_cvt_pk_bf16_f32 v130, v68, v69
	v_cvt_pk_bf16_f32 v131, v70, v71
	s_waitcnt lgkmcnt(4)
	v_mfma_f32_32x32x16_bf16 v[80:95], v[164:167], v[124:127], 0
	ds_read_b64_tr_b16 v[34:35], v38 offset:25600
	ds_read_b64_tr_b16 v[36:37], v38 offset:26112
	v_add_f32_e32 v39, v74, v39
	v_add_f32_e32 v39, v75, v39
	v_add_f32_e32 v39, v76, v39
	v_add_f32_e32 v39, v77, v39
	v_cvt_pk_bf16_f32 v136, v72, v73
	v_cvt_pk_bf16_f32 v137, v74, v75
	v_mfma_f32_32x32x16_bf16 v[96:111], v[168:171], v[120:123], v[96:111]
	ds_read_b64_tr_b16 v[70:71], v38 offset:29696
	ds_read_b64_tr_b16 v[72:73], v38 offset:30208
	v_add_f32_e32 v39, v78, v39
	v_add_f32_e32 v39, v79, v39
	v_add_f32_e32 v39, v48, v39
	v_add_f32_e32 v39, v49, v39
	v_cvt_pk_bf16_f32 v138, v76, v77
	v_cvt_pk_bf16_f32 v139, v78, v79
	v_mfma_f32_32x32x16_bf16 v[80:95], v[160:163], v[120:123], v[80:95]
	ds_read_b64_tr_b16 v[120:121], v38 offset:26624
	ds_read_b64_tr_b16 v[122:123], v38 offset:27136
	v_add_f32_e32 v39, v50, v39
	v_add_f32_e32 v39, v51, v39
	v_add_f32_e32 v39, v52, v39
	v_add_f32_e32 v39, v53, v39
	v_cvt_pk_bf16_f32 v132, v48, v49
	v_cvt_pk_bf16_f32 v133, v50, v51
	v_mfma_f32_32x32x16_bf16 v[96:111], v[156:159], v[116:119], v[96:111]
	ds_read_b64_tr_b16 v[66:67], v38 offset:30720
	ds_read_b64_tr_b16 v[68:69], v38 offset:31232
	v_add_f32_e32 v39, v54, v39
	v_add_f32_e32 v39, v55, v39
	v_add_f32_e32 v39, v56, v39
	v_add_f32_e32 v39, v57, v39
	v_cvt_pk_bf16_f32 v134, v52, v53
	v_cvt_pk_bf16_f32 v135, v54, v55
	v_mfma_f32_32x32x16_bf16 v[80:95], v[152:155], v[116:119], v[80:95]
	ds_read_b64_tr_b16 v[74:75], v38 offset:27648
	ds_read_b64_tr_b16 v[76:77], v38 offset:28160
	v_add_f32_e32 v39, v58, v39
	v_add_f32_e32 v39, v59, v39
	v_add_f32_e32 v39, v60, v39
	v_add_f32_e32 v39, v61, v39
	v_cvt_pk_bf16_f32 v140, v56, v57
	v_cvt_pk_bf16_f32 v141, v58, v59
	v_mfma_f32_32x32x16_bf16 v[96:111], v[148:151], v[112:115], v[96:111]
	ds_read_b64_tr_b16 v[116:117], v38 offset:31744
	ds_read_b64_tr_b16 v[118:119], v38 offset:32256
	v_add_f32_e32 v38, v62, v39
	v_add_f32_e32 v38, v63, v38
	v_add_f32_e32 v78, 0, v38
	v_cvt_pk_bf16_f32 v142, v60, v61
	v_cvt_pk_bf16_f32 v143, v62, v63
	v_mfma_f32_32x32x16_bf16 v[80:95], v[144:147], v[112:115], v[80:95]
	s_lshl_b32 s4, s67, 2
	s_add_i32 s4, s4, 0
	s_add_i32 s4, s4, 0x14800
	v_add_u32_e32 v38, s4, v230
	v_add_u32_e32 v79, 0xffffff00, v38
	ds_read_b128 v[38:41], v79
	ds_read_b128 v[42:45], v79 offset:32
	ds_read_b128 v[46:49], v79 offset:64
	ds_read_b128 v[50:53], v79 offset:96
	ds_read_b128 v[54:57], v79 offset:128
	ds_read_b128 v[58:61], v79 offset:160
	ds_read_b128 v[62:65], v79 offset:192
	ds_read_b128 v[112:115], v79 offset:224
	s_waitcnt lgkmcnt(7)
	v_sub_f32_e32 v39, v206, v39
	s_waitcnt lgkmcnt(3)
	v_sub_f32_e32 v55, v206, v55
	v_sub_f32_e32 v54, v206, v54
	v_pk_add_f32 v[54:55], v[80:81], v[54:55]
	v_or_b32_e32 v80, 0xe0, v228
	v_sub_f32_e32 v38, v206, v38
	v_or_b32_e32 v79, 0xc0, v228
	v_cmp_le_i32_e32 vcc, v80, v231
	v_pk_add_f32 v[38:39], v[96:97], v[38:39]
	v_sub_f32_e32 v41, v206, v41
	v_cndmask_b32_e32 v80, v223, v54, vcc
	v_cmp_lt_i32_e32 vcc, v79, v231
	v_sub_f32_e32 v40, v206, v40
	s_waitcnt lgkmcnt(2)
	v_sub_f32_e32 v61, v206, v61
	v_cndmask_b32_e32 v81, v223, v39, vcc
	v_cmp_le_i32_e32 vcc, v79, v231
	v_sub_f32_e32 v60, v206, v60
	v_pk_add_f32 v[40:41], v[98:99], v[40:41]
	v_cndmask_b32_e32 v79, v223, v38, vcc
	v_or_b32_e32 v38, 0xe1, v228
	v_cmp_le_i32_e32 vcc, v38, v231
	v_or_b32_e32 v38, 0xc2, v228
	v_sub_f32_e32 v57, v206, v57
	v_sub_f32_e32 v56, v206, v56
	v_pk_add_f32 v[60:61], v[86:87], v[60:61]
	v_cndmask_b32_e32 v86, v223, v55, vcc
	v_cmp_le_i32_e32 vcc, v38, v231
	v_or_b32_e32 v38, 0xe2, v228
	s_waitcnt lgkmcnt(1)
; #define SBAR() __builtin_amdgcn_sched_barrier(0)
;   #define RESC() do{}while(0)
;   #define PKW(P,B) cvtpk_s(P[B],P[B+1])
; template<int THRL> __device__ __forceinline__ void attn_unit(int b,int h,int qb,int t0,float cqv,float mfix,const float*__restrict__ cf,float cref,unsigned*counter,const bf16*Q,const bf16*__restrict__ K,const bf16*__restrict__ V,bf16*O,const bf16*__restrict__ G,char*shm){
;     ...
;   STEP(pB0,pB1,pA0,pA1,NT-1,false,false,false); RESC();
;   { float sacc=pB0[0]+pB0[1]; _Pragma("unroll") for(int r=2;r<16;++r)sacc+=pB0[r]; _Pragma("unroll") for(int r=0;r<16;++r)sacc+=pB1[r]; l_reg+=sacc;
;     pw0=(u32x4){PKW(pB0,0),PKW(pB0,2),PKW(pB0,4),PKW(pB0,6)};pw1=(u32x4){PKW(pB0,8),PKW(pB0,10),PKW(pB0,12),PKW(pB0,14)};pw2=(u32x4){PKW(pB1,0),PKW(pB1,2),PKW(pB1,4),PKW(pB1,6)};pw3=(u32x4){PKW(pB1,8),PKW(pB1,10),PKW(pB1,12),PKW(pB1,14)};
;     SBAR(); pv(o,vb0+sl_cur,PAF(0),PAF(1),PAF(2),PAF(3)); }
	v_sub_f32_e32 v63, v206, v63
	v_sub_f32_e32 v62, v206, v62
	v_pk_add_f32 v[56:57], v[82:83], v[56:57]
	v_cndmask_b32_e32 v87, v223, v40, vcc
	v_cmp_le_i32_e32 vcc, v38, v231
	v_or_b32_e32 v38, 0xc3, v228
	v_pk_add_f32 v[62:63], v[88:89], v[62:63]
	v_cndmask_b32_e32 v88, v223, v56, vcc
	v_cmp_le_i32_e32 vcc, v38, v231
	v_or_b32_e32 v38, 0xe3, v228
	v_sub_f32_e32 v43, v206, v43
	v_sub_f32_e32 v42, v206, v42
	v_sub_f32_e32 v65, v206, v65
	v_sub_f32_e32 v64, v206, v64
	v_cndmask_b32_e32 v89, v223, v41, vcc
	v_cmp_le_i32_e32 vcc, v38, v231
	v_or_b32_e32 v38, 0xc8, v228
	v_pk_add_f32 v[42:43], v[100:101], v[42:43]
	v_sub_f32_e32 v59, v206, v59
	v_sub_f32_e32 v58, v206, v58
	v_pk_add_f32 v[64:65], v[90:91], v[64:65]
	v_cndmask_b32_e32 v90, v223, v57, vcc
	v_cmp_le_i32_e32 vcc, v38, v231
	v_or_b32_e32 v38, 0xe8, v228
	v_pk_add_f32 v[58:59], v[84:85], v[58:59]
	v_cndmask_b32_e32 v54, v223, v42, vcc
	v_cmp_le_i32_e32 vcc, v38, v231
	v_or_b32_e32 v39, 0xc9, v228
	v_sub_f32_e32 v45, v206, v45
	v_cndmask_b32_e32 v38, v223, v58, vcc
	v_cmp_le_i32_e32 vcc, v39, v231
	v_or_b32_e32 v39, 0xe9, v228
	v_sub_f32_e32 v44, v206, v44
	v_cndmask_b32_e32 v55, v223, v43, vcc
	v_cmp_le_i32_e32 vcc, v39, v231
	v_or_b32_e32 v40, 0xca, v228
	v_pk_add_f32 v[44:45], v[102:103], v[44:45]
	v_cndmask_b32_e32 v39, v223, v59, vcc
	v_cmp_le_i32_e32 vcc, v40, v231
	v_or_b32_e32 v40, 0xea, v228
	v_or_b32_e32 v41, 0xcb, v228
	v_cndmask_b32_e32 v56, v223, v44, vcc
	v_cmp_le_i32_e32 vcc, v40, v231
	v_sub_f32_e32 v47, v206, v47
	v_sub_f32_e32 v46, v206, v46
	v_cndmask_b32_e32 v40, v223, v60, vcc
	v_cmp_le_i32_e32 vcc, v41, v231
	v_or_b32_e32 v41, 0xeb, v228
	v_or_b32_e32 v42, 0xd0, v228
	v_cndmask_b32_e32 v57, v223, v45, vcc
	v_cmp_le_i32_e32 vcc, v41, v231
	v_pk_add_f32 v[46:47], v[104:105], v[46:47]
	v_or_b32_e32 v43, 0xd1, v228
	v_cndmask_b32_e32 v41, v223, v61, vcc
	v_cmp_le_i32_e32 vcc, v42, v231
	v_or_b32_e32 v42, 0xf0, v228
	v_sub_f32_e32 v49, v206, v49
	v_cndmask_b32_e32 v58, v223, v46, vcc
	v_cmp_le_i32_e32 vcc, v42, v231
	v_sub_f32_e32 v48, v206, v48
	v_or_b32_e32 v44, 0xd2, v228
	v_cndmask_b32_e32 v42, v223, v62, vcc
	v_cmp_le_i32_e32 vcc, v43, v231
	v_or_b32_e32 v43, 0xf1, v228
	v_pk_add_f32 v[48:49], v[106:107], v[48:49]
	v_cndmask_b32_e32 v59, v223, v47, vcc
	v_cmp_le_i32_e32 vcc, v43, v231
	v_or_b32_e32 v45, 0xd3, v228
	v_sub_f32_e32 v51, v206, v51
	v_cndmask_b32_e32 v43, v223, v63, vcc
	v_cmp_le_i32_e32 vcc, v44, v231
	v_or_b32_e32 v44, 0xf2, v228
	v_sub_f32_e32 v50, v206, v50
	v_cndmask_b32_e32 v60, v223, v48, vcc
	v_cmp_le_i32_e32 vcc, v44, v231
	v_or_b32_e32 v46, 0xd8, v228
	v_pk_add_f32 v[50:51], v[108:109], v[50:51]
	v_cndmask_b32_e32 v44, v223, v64, vcc
	v_cmp_le_i32_e32 vcc, v45, v231
	v_or_b32_e32 v45, 0xf3, v228
	s_waitcnt lgkmcnt(0)
	v_sub_f32_e32 v99, v206, v113
	v_cndmask_b32_e32 v61, v223, v49, vcc
	v_cmp_le_i32_e32 vcc, v45, v231
	v_sub_f32_e32 v98, v206, v112
	v_pk_add_f32 v[82:83], v[92:93], v[98:99]
	v_cndmask_b32_e32 v45, v223, v65, vcc
	v_cmp_le_i32_e32 vcc, v46, v231
	v_or_b32_e32 v46, 0xf8, v228
	v_or_b32_e32 v47, 0xd9, v228
	v_cndmask_b32_e32 v62, v223, v50, vcc
	v_cmp_le_i32_e32 vcc, v46, v231
	v_sub_f32_e32 v53, v206, v53
	v_sub_f32_e32 v52, v206, v52
	v_cndmask_b32_e32 v46, v223, v82, vcc
	v_cmp_le_i32_e32 vcc, v47, v231
	v_or_b32_e32 v47, 0xf9, v228
	v_or_b32_e32 v48, 0xda, v228
	v_cndmask_b32_e32 v63, v223, v51, vcc
	v_cmp_le_i32_e32 vcc, v47, v231
	v_pk_add_f32 v[52:53], v[110:111], v[52:53]
	v_sub_f32_e32 v97, v206, v115
	v_sub_f32_e32 v96, v206, v114
	v_cndmask_b32_e32 v47, v223, v83, vcc
	v_cmp_le_i32_e32 vcc, v48, v231
	v_or_b32_e32 v48, 0xfa, v228
	v_pk_add_f32 v[84:85], v[94:95], v[96:97]
	v_cndmask_b32_e32 v64, v223, v52, vcc
	v_cmp_le_i32_e32 vcc, v48, v231
	v_or_b32_e32 v49, 0xdb, v228
	s_nop 0
	v_cndmask_b32_e32 v48, v223, v84, vcc
	v_cmp_le_i32_e32 vcc, v49, v231
	v_or_b32_e32 v49, 0xfb, v228
	s_nop 0
	v_cndmask_b32_e32 v65, v223, v53, vcc
	v_cmp_le_i32_e32 vcc, v49, v231
	s_nop 1
	v_cndmask_b32_e32 v49, v223, v85, vcc
	v_mfma_f32_32x32x16_bf16 v[0:15], v[128:131], v[176:179], v[0:15]
	v_exp_f32_e32 v50, v79
	v_exp_f32_e32 v51, v81
	v_exp_f32_e32 v52, v87
	v_exp_f32_e32 v53, v89
	v_mfma_f32_32x32x16_bf16 v[16:31], v[128:131], v[172:175], v[16:31]
	v_exp_f32_e32 v54, v54
	v_exp_f32_e32 v55, v55
	v_exp_f32_e32 v56, v56
	v_exp_f32_e32 v57, v57
	v_mfma_f32_32x32x16_bf16 v[0:15], v[136:139], v[34:37], v[0:15]
	v_exp_f32_e32 v58, v58
	v_exp_f32_e32 v59, v59
	v_exp_f32_e32 v60, v60
	v_exp_f32_e32 v61, v61
	v_mfma_f32_32x32x16_bf16 v[16:31], v[136:139], v[70:73], v[16:31]
	v_exp_f32_e32 v62, v62
	v_exp_f32_e32 v63, v63
	v_exp_f32_e32 v64, v64
	v_exp_f32_e32 v65, v65
	v_mfma_f32_32x32x16_bf16 v[0:15], v[132:135], v[120:123], v[0:15]
	v_exp_f32_e32 v34, v80
	v_exp_f32_e32 v35, v86
	v_exp_f32_e32 v36, v88
	v_exp_f32_e32 v37, v90
	v_mfma_f32_32x32x16_bf16 v[16:31], v[132:135], v[66:69], v[16:31]
	v_exp_f32_e32 v38, v38
	v_exp_f32_e32 v39, v39
	v_exp_f32_e32 v40, v40
	v_exp_f32_e32 v41, v41
	v_mfma_f32_32x32x16_bf16 v[0:15], v[140:143], v[74:77], v[0:15]
	v_exp_f32_e32 v42, v42
	v_exp_f32_e32 v43, v43
	v_exp_f32_e32 v44, v44
	v_exp_f32_e32 v45, v45
	v_mfma_f32_32x32x16_bf16 v[16:31], v[140:143], v[116:119], v[16:31]
	v_exp_f32_e32 v46, v46
	v_exp_f32_e32 v47, v47
	v_exp_f32_e32 v48, v48
	v_exp_f32_e32 v49, v49
	v_cvt_pk_bf16_f32 v66, v50, v51
	v_cvt_pk_bf16_f32 v67, v52, v53
	v_cvt_pk_bf16_f32 v68, v54, v55
	v_cvt_pk_bf16_f32 v69, v56, v57
	v_cvt_pk_bf16_f32 v70, v58, v59
	v_cvt_pk_bf16_f32 v71, v60, v61
	v_cvt_pk_bf16_f32 v72, v62, v63
	v_cvt_pk_bf16_f32 v73, v64, v65
	v_cvt_pk_bf16_f32 v74, v34, v35
	v_cvt_pk_bf16_f32 v75, v36, v37
	v_cvt_pk_bf16_f32 v76, v38, v39
	v_cvt_pk_bf16_f32 v77, v40, v41
	v_cvt_pk_bf16_f32 v80, v42, v43
	v_cvt_pk_bf16_f32 v81, v44, v45
	v_cvt_pk_bf16_f32 v82, v46, v47
	v_cvt_pk_bf16_f32 v83, v48, v49
	v_add3_u32 v33, v33, v229, s59
	ds_read_b64_tr_b16 v[84:85],v33 offset:0
	ds_read_b64_tr_b16 v[86:87],v33 offset:512
	ds_read_b64_tr_b16 v[88:89],v33 offset:1024
	ds_read_b64_tr_b16 v[90:91],v33 offset:1536
	ds_read_b64_tr_b16 v[92:93],v33 offset:2048
	ds_read_b64_tr_b16 v[94:95],v33 offset:2560
	ds_read_b64_tr_b16 v[96:97],v33 offset:3072
	ds_read_b64_tr_b16 v[98:99],v33 offset:3584
	s_waitcnt lgkmcnt(0)
; __device__ __forceinline__ int crow(int r,int hi){return (r&3)+8*(r>>2)+4*hi;}
; #define SBAR() __builtin_amdgcn_sched_barrier(0)
;   #define PKW(P,B) cvtpk_s(P[B],P[B+1])
; __device__ __forceinline__ void pv(f32x16*o,int vb,bf16x8 pa0,bf16x8 pa1,bf16x8 pa2,bf16x8 pa3){
;     ...
;     o[d0]=__builtin_amdgcn_mfma_f32_32x32x16_bf16(pa0,PK(0),o[d0],0,0,0);
;     o[d0]=__builtin_amdgcn_mfma_f32_32x32x16_bf16(pa1,PK(1),o[d0],0,0,0);
;     o[d0]=__builtin_amdgcn_mfma_f32_32x32x16_bf16(pa2,PK(2),o[d0],0,0,0);
;     o[d0]=__builtin_amdgcn_mfma_f32_32x32x16_bf16(pa3,PK(3),o[d0],0,0,0);
; template<int THRL> __device__ __forceinline__ void attn_unit(int b,int h,int qb,int t0,float cqv,float mfix,const float*__restrict__ cf,float cref,unsigned*counter,const bf16*Q,const bf16*__restrict__ K,const bf16*__restrict__ V,bf16*O,const bf16*__restrict__ G,char*shm){
;     ...
;   { float sacc=pB0[0]+pB0[1]; _Pragma("unroll") for(int r=2;r<16;++r)sacc+=pB0[r]; _Pragma("unroll") for(int r=0;r<16;++r)sacc+=pB1[r]; l_reg+=sacc;
;     pw0=(u32x4){PKW(pB0,0),PKW(pB0,2),PKW(pB0,4),PKW(pB0,6)};pw1=(u32x4){PKW(pB0,8),PKW(pB0,10),PKW(pB0,12),PKW(pB0,14)};pw2=(u32x4){PKW(pB1,0),PKW(pB1,2),PKW(pB1,4),PKW(pB1,6)};pw3=(u32x4){PKW(pB1,8),PKW(pB1,10),PKW(pB1,12),PKW(pB1,14)};
;     SBAR(); pv(o,vb0+sl_cur,PAF(0),PAF(1),PAF(2),PAF(3)); }
;     ...
;   int unext_=0; if(tid==0) unext_=(int)atomicAdd(counter,1u);
;   {auto rr=__builtin_amdgcn_permlane32_swap(__float_as_uint(l_reg),__float_as_uint(l_reg),false,false);l_reg=__uint_as_float(rr[0])+__uint_as_float(rr[1]);}
;   if(hi==0)wsf[32+r32]=l_reg;asm volatile("s_waitcnt lgkmcnt(0)":::"memory");
;   float rli[16];
;   #pragma unroll
;   for(int r=0;r<16;++r)rli[r]=__builtin_amdgcn_rcpf(wsf[32+crow(r,hi)]);
;   bf16*Ow=O+(rowbase+q0+wid*QBLK)*DM+h*D;
;   { bf16*stg=(bf16*)(shm+LDS_OST)+wid*2048;
;     #pragma unroll
;     for(int r=0;r<16;++r){const int orow=crow(r,hi);
;       #pragma unroll
;       for(int d0=0;d0<2;++d0)stg[orow*64+d0*32+r32]=__float2bfloat16(o[d0][r]*rli[r]);}
	s_nop 0
	v_mfma_f32_32x32x16_bf16 v[0:15], v[66:69], v[84:87], v[0:15]
	ds_read_b64_tr_b16 v[84:85],v33 offset:4096
	ds_read_b64_tr_b16 v[86:87],v33 offset:4608
	v_mfma_f32_32x32x16_bf16 v[0:15], v[70:73], v[88:91], v[0:15]
	ds_read_b64_tr_b16 v[88:89],v33 offset:5120
	ds_read_b64_tr_b16 v[90:91],v33 offset:5632
	v_mfma_f32_32x32x16_bf16 v[0:15], v[74:77], v[92:95], v[0:15]
	ds_read_b64_tr_b16 v[92:93],v33 offset:6144
	ds_read_b64_tr_b16 v[94:95],v33 offset:6656
	v_mfma_f32_32x32x16_bf16 v[0:15], v[80:83], v[96:99], v[0:15]
	ds_read_b64_tr_b16 v[96:97],v33 offset:7168
	ds_read_b64_tr_b16 v[98:99],v33 offset:7680
	s_waitcnt lgkmcnt(0)
	v_mfma_f32_32x32x16_bf16 v[16:31], v[66:69], v[84:87], v[16:31]
	v_cmp_eq_u32_e32 vcc, 0, v226
	v_mov_b32_e32 v33, 0
	v_mfma_f32_32x32x16_bf16 v[16:31], v[70:73], v[88:91], v[16:31]
	v_mfma_f32_32x32x16_bf16 v[16:31], v[74:77], v[92:95], v[16:31]
	v_mfma_f32_32x32x16_bf16 v[16:31], v[80:83], v[96:99], v[16:31]
	v_add_f32_e32 v50, v50, v51
	v_add_f32_e32 v50, v52, v50
	v_add_f32_e32 v50, v53, v50
	v_add_f32_e32 v50, v54, v50
	v_add_f32_e32 v50, v55, v50
	v_add_f32_e32 v50, v56, v50
	v_add_f32_e32 v50, v57, v50
	v_add_f32_e32 v50, v58, v50
	v_add_f32_e32 v50, v59, v50
	v_add_f32_e32 v50, v60, v50
	v_add_f32_e32 v50, v61, v50
	v_add_f32_e32 v50, v62, v50
	v_add_f32_e32 v50, v63, v50
	v_add_f32_e32 v50, v64, v50
	v_add_f32_e32 v50, v65, v50
	v_add_f32_e32 v34, v34, v50
	v_add_f32_e32 v34, v35, v34
	v_add_f32_e32 v34, v36, v34
	v_add_f32_e32 v34, v37, v34
	v_add_f32_e32 v34, v38, v34
	v_add_f32_e32 v34, v39, v34
	v_add_f32_e32 v34, v40, v34
	v_add_f32_e32 v34, v41, v34
	v_add_f32_e32 v34, v42, v34
	v_add_f32_e32 v34, v43, v34
	v_add_f32_e32 v34, v44, v34
	v_add_f32_e32 v34, v45, v34
	v_add_f32_e32 v34, v46, v34
	v_add_f32_e32 v34, v47, v34
	v_add_f32_e32 v34, v48, v34
	v_add_f32_e32 v34, v49, v34
	v_add_f32_e32 v32, v32, v78
	v_add_f32_e32 v32, v32, v34
	s_and_b32 s4, s66, 0x3fffffc0
	s_lshl_b32 s4, s4, 2
	v_mov_b32_e32 v34, v32
	s_add_i32 s16, s4, 0
	s_nop 0
	v_permlane32_swap_b32_e32 v32, v34
	v_cmp_gt_u32_e64 s[4:5], 32, v224
	s_and_saveexec_b64 s[18:19], s[4:5]
	v_lshl_add_u32 v35, v204, 2, s16
	v_add_f32_e32 v32, v32, v34
	ds_write_b32 v35, v32 offset:49280
	s_or_b64 exec, exec, s[18:19]
	s_waitcnt lgkmcnt(0)
	v_lshl_add_u32 v32, v228, 2, s16
	ds_read_b128 v[34:37], v32 offset:49280
	ds_read_b128 v[38:41], v32 offset:49312
	s_lshl_b64 s[4:5], s[38:39], 1
	s_add_u32 s14, s12, s4
	s_addc_u32 s15, s13, s5
	s_waitcnt lgkmcnt(1)
	v_rcp_f32_e32 v42, v34
	v_rcp_f32_e32 v43, v35
	v_rcp_f32_e32 v44, v36
	v_rcp_f32_e32 v45, v37
	s_waitcnt lgkmcnt(0)
	v_rcp_f32_e32 v46, v38
	ds_read_b128 v[34:37], v32 offset:49344
	v_rcp_f32_e32 v47, v39
	v_rcp_f32_e32 v48, v40
	v_rcp_f32_e32 v49, v41
	ds_read_b128 v[38:41], v32 offset:49376
	s_lshl_b32 s16, s65, 12
	s_waitcnt lgkmcnt(1)
	v_rcp_f32_e32 v32, v34
	v_rcp_f32_e32 v34, v35
	v_rcp_f32_e32 v35, v36
	v_rcp_f32_e32 v36, v37
	s_waitcnt lgkmcnt(0)
	v_rcp_f32_e32 v37, v38
	v_rcp_f32_e32 v38, v39
	v_rcp_f32_e32 v39, v40
	v_rcp_f32_e32 v40, v41
	s_add_i32 s16, s16, 0
	v_lshlrev_b32_e32 v41, 1, v204
	v_lshlrev_b32_e32 v50, 9, v227
	v_mul_f32_e32 v0, v0, v42
	v_add3_u32 v41, s16, v41, v50
	v_cvt_pk_bf16_f32 v0, v0, s0
	ds_write_b16 v41, v0 offset:51200
	v_mul_f32_e32 v0, v16, v42
	v_cvt_pk_bf16_f32 v0, v0, s0
	ds_write_b16 v41, v0 offset:51264
	v_mul_f32_e32 v0, v1, v43
	v_cvt_pk_bf16_f32 v0, v0, s0
	ds_write_b16 v41, v0 offset:51328
	v_mul_f32_e32 v0, v17, v43
	v_cvt_pk_bf16_f32 v0, v0, s0
	ds_write_b16 v41, v0 offset:51392
	v_mul_f32_e32 v0, v2, v44
	v_cvt_pk_bf16_f32 v0, v0, s0
	ds_write_b16 v41, v0 offset:51456
	v_mul_f32_e32 v0, v18, v44
	v_cvt_pk_bf16_f32 v0, v0, s0
	ds_write_b16 v41, v0 offset:51520
	v_mul_f32_e32 v0, v3, v45
	v_cvt_pk_bf16_f32 v0, v0, s0
	ds_write_b16 v41, v0 offset:51584
	v_mul_f32_e32 v0, v19, v45
	v_cvt_pk_bf16_f32 v0, v0, s0
	ds_write_b16 v41, v0 offset:51648
	v_mul_f32_e32 v0, v4, v46
	v_cvt_pk_bf16_f32 v0, v0, s0
	ds_write_b16 v41, v0 offset:52224
	v_mul_f32_e32 v0, v20, v46
	v_cvt_pk_bf16_f32 v0, v0, s0
	ds_write_b16 v41, v0 offset:52288
	v_mul_f32_e32 v0, v5, v47
	v_cvt_pk_bf16_f32 v0, v0, s0
	ds_write_b16 v41, v0 offset:52352
	v_mul_f32_e32 v0, v21, v47
	v_cvt_pk_bf16_f32 v0, v0, s0
	ds_write_b16 v41, v0 offset:52416
	v_mul_f32_e32 v0, v6, v48
	v_cvt_pk_bf16_f32 v0, v0, s0
	ds_write_b16 v41, v0 offset:52480
	v_mul_f32_e32 v0, v22, v48
	v_cvt_pk_bf16_f32 v0, v0, s0
	ds_write_b16 v41, v0 offset:52544
	v_mul_f32_e32 v0, v7, v49
	v_cvt_pk_bf16_f32 v0, v0, s0
	ds_write_b16 v41, v0 offset:52608
	v_mul_f32_e32 v0, v23, v49
	v_cvt_pk_bf16_f32 v0, v0, s0
	ds_write_b16 v41, v0 offset:52672
	v_mul_f32_e32 v0, v8, v32
	v_cvt_pk_bf16_f32 v0, v0, s0
	ds_write_b16 v41, v0 offset:53248
	v_mul_f32_e32 v0, v24, v32
	v_cvt_pk_bf16_f32 v0, v0, s0
	ds_write_b16 v41, v0 offset:53312
	v_mul_f32_e32 v0, v9, v34
	v_cvt_pk_bf16_f32 v0, v0, s0
	ds_write_b16 v41, v0 offset:53376
	v_mul_f32_e32 v0, v25, v34
	v_cvt_pk_bf16_f32 v0, v0, s0
	ds_write_b16 v41, v0 offset:53440
	v_mul_f32_e32 v0, v10, v35
	v_cvt_pk_bf16_f32 v0, v0, s0
	ds_write_b16 v41, v0 offset:53504
	v_mul_f32_e32 v0, v26, v35
	v_cvt_pk_bf16_f32 v0, v0, s0
	ds_write_b16 v41, v0 offset:53568
	v_mul_f32_e32 v0, v11, v36
	v_cvt_pk_bf16_f32 v0, v0, s0
	ds_write_b16 v41, v0 offset:53632
	v_mul_f32_e32 v0, v27, v36
	v_cvt_pk_bf16_f32 v0, v0, s0
	ds_write_b16 v41, v0 offset:53696
	v_mul_f32_e32 v0, v12, v37
	v_cvt_pk_bf16_f32 v0, v0, s0
	ds_write_b16 v41, v0 offset:54272
	v_mul_f32_e32 v0, v28, v37
	v_cvt_pk_bf16_f32 v0, v0, s0
	ds_write_b16 v41, v0 offset:54336
	v_mul_f32_e32 v0, v13, v38
	v_cvt_pk_bf16_f32 v0, v0, s0
	ds_write_b16 v41, v0 offset:54400
	v_mul_f32_e32 v0, v29, v38
	v_cvt_pk_bf16_f32 v0, v0, s0
	ds_write_b16 v41, v0 offset:54464
	v_mul_f32_e32 v0, v14, v39
	v_cvt_pk_bf16_f32 v0, v0, s0
	ds_write_b16 v41, v0 offset:54528
	v_mul_f32_e32 v0, v30, v39
	v_cvt_pk_bf16_f32 v0, v0, s0
	ds_write_b16 v41, v0 offset:54592
	v_mul_f32_e32 v0, v15, v40
	v_cvt_pk_bf16_f32 v0, v0, s0
	ds_write_b16 v41, v0 offset:54656
	v_mul_f32_e32 v0, v31, v40
	s_add_u32 s4, s2, s4
	v_cvt_pk_bf16_f32 v0, v0, s0
	s_addc_u32 s5, s3, s5
	ds_write_b16 v41, v0 offset:54720
	s_add_u32 s4, s4, s52
	v_lshlrev_b32_e32 v0, 1, v225
	s_addc_u32 s5, s5, s53
	v_and_b32_e32 v204, 0x70, v0
	v_lshlrev_b32_e32 v2, 8, v224
	v_lshl_add_u64 v[0:1], s[4:5], 0, v[204:205]
	v_and_b32_e32 v2, 0x3800, v2
	v_mov_b32_e32 v3, v205
	s_waitcnt lgkmcnt(0)
; __device__ __forceinline__ unsigned cvtpk_s(float lo,float hi){f32x2_t v={lo,hi};bf16x2_t b=__builtin_convertvector(v,bf16x2_t);return __builtin_bit_cast(unsigned,b);}
; template<int THRL> __device__ __forceinline__ void attn_unit(int b,int h,int qb,int t0,float cqv,float mfix,const float*__restrict__ cf,float cref,unsigned*counter,const bf16*Q,const bf16*__restrict__ K,const bf16*__restrict__ V,bf16*O,const bf16*__restrict__ G,char*shm){
;     ...
;     const bf16*Gw=G+(rowbase+q0+wid*QBLK)*DM+h*D;
;     u32x4 gv4[4];
;     #pragma unroll
;     for(int i=0;i<4;++i)gv4[i]=*(const u32x4*)(Gw+(long)(i*8+(lane>>3))*DM+(lane&7)*8);
;     #pragma unroll
;     for(int i=0;i<4;++i){const int row=i*8+(lane>>3),ch=lane&7; const u32x4 v=*(const u32x4*)(stg+row*64+ch*8); const u32x4 gv=gv4[i]; u32x4 w;
;       #pragma unroll
;       for(int c=0;c<4;++c){ const float ol=__uint_as_float(v[c]<<16), oh=__uint_as_float(v[c]&0xffff0000u), gl=__uint_as_float(gv[c]<<16), gh=__uint_as_float(gv[c]&0xffff0000u);
;         const float rl=ol*gl*__builtin_amdgcn_rcpf(1.f+__expf(-gl)), rh=oh*gh*__builtin_amdgcn_rcpf(1.f+__expf(-gh)); w[c]=cvtpk_s(rl,rh); }
;       ATTN_STORE16(Ow+(long)row*DM+ch*8,w);} }
	v_lshl_add_u64 v[0:1], v[0:1], 0, v[2:3]
	s_waitcnt vmcnt(0)
	v_mov_b64_e32 v[14:15], v[180:181]
	v_mov_b64_e32 v[16:17], v[182:183]
	s_movk_i32 s4, 0x4000
	v_add_co_u32_e64 v2, s[4:5], s4, v0
	v_lshrrev_b32_e32 v32, 3, v224
	s_nop 0
	v_addc_co_u32_e64 v3, s[4:5], 0, v1, s[4:5]
	v_mov_b64_e32 v[8:9], v[184:185]
	v_mov_b64_e32 v[10:11], v[186:187]
	s_mov_b32 s4, 0x8000
	v_add_co_u32_e64 v2, s[4:5], s4, v0
	v_add_u32_e32 v34, s16, v204
	s_nop 0
	v_addc_co_u32_e64 v3, s[4:5], 0, v1, s[4:5]
	s_mov_b32 s4, 0xc000
	s_nop 0
	v_add_co_u32_e64 v0, s[4:5], s4, v0
	v_lshl_add_u32 v18, v32, 7, v34
	s_nop 0
	v_addc_co_u32_e64 v1, s[4:5], 0, v1, s[4:5]
	v_mov_b64_e32 v[4:5], v[188:189]
	v_mov_b64_e32 v[6:7], v[190:191]
	s_nop 0
	v_mov_b64_e32 v[0:1], v[192:193]
	v_mov_b64_e32 v[2:3], v[194:195]
	v_or_b32_e32 v35, 8, v32
	s_add_u32 s4, s14, s52
	s_addc_u32 s5, s15, s53
	v_lshl_add_u64 v[12:13], s[4:5], 0, v[204:205]
	v_lshlrev_b32_e32 v204, 11, v32
	s_waitcnt vmcnt(3)
	v_lshlrev_b32_e32 v26, 16, v14
	v_and_b32_e32 v29, 0xffff0000, v14
	v_mul_f32_e32 v14, 0xbfb8aa3b, v26
	v_exp_f32_e32 v14, v14
	v_mul_f32_e32 v19, 0xbfb8aa3b, v29
	v_exp_f32_e32 v22, v19
	ds_read_b128 v[18:21], v18 offset:51200
	v_add_f32_e32 v14, 1.0, v14
	v_rcp_f32_e32 v30, v14
	v_add_f32_e32 v14, 1.0, v22
	v_rcp_f32_e32 v31, v14
	v_lshl_add_u32 v14, v35, 7, v34
	ds_read_b128 v[22:25], v14 offset:51200
	s_waitcnt lgkmcnt(1)
	v_and_b32_e32 v27, 0xffff0000, v18
	v_lshlrev_b32_e32 v28, 16, v18
	v_pk_mul_f32 v[26:27], v[28:29], v[26:27]
	v_lshlrev_b32_e32 v28, 16, v15
	v_pk_mul_f32 v[26:27], v[30:31], v[26:27]
	v_and_b32_e32 v31, 0xffff0000, v15
	v_mul_f32_e32 v14, 0xbfb8aa3b, v28
	v_exp_f32_e32 v15, v14
	v_mul_f32_e32 v14, 0xbfb8aa3b, v31
	v_exp_f32_e32 v18, v14
	v_cvt_pk_bf16_f32 v14, v26, v27
	v_add_f32_e32 v15, 1.0, v15
	v_rcp_f32_e32 v26, v15
	v_add_f32_e32 v15, 1.0, v18
	v_rcp_f32_e32 v27, v15
	v_and_b32_e32 v29, 0xffff0000, v19
	v_lshlrev_b32_e32 v30, 16, v19
	v_pk_mul_f32 v[18:19], v[30:31], v[28:29]
	v_and_b32_e32 v29, 0xffff0000, v16
	v_pk_mul_f32 v[18:19], v[26:27], v[18:19]
	v_lshlrev_b32_e32 v26, 16, v16
	v_mul_f32_e32 v15, 0xbfb8aa3b, v26
	v_exp_f32_e32 v16, v15
	v_mul_f32_e32 v15, 0xbfb8aa3b, v29
	v_exp_f32_e32 v27, v15
	v_cvt_pk_bf16_f32 v15, v18, v19
	v_add_f32_e32 v16, 1.0, v16
	v_rcp_f32_e32 v18, v16
	v_add_f32_e32 v16, 1.0, v27
	v_rcp_f32_e32 v19, v16
	v_and_b32_e32 v27, 0xffff0000, v20
	v_lshlrev_b32_e32 v28, 16, v20
	v_pk_mul_f32 v[26:27], v[28:29], v[26:27]
	v_and_b32_e32 v29, 0xffff0000, v17
	v_pk_mul_f32 v[18:19], v[18:19], v[26:27]
	v_lshlrev_b32_e32 v26, 16, v17
	v_mul_f32_e32 v16, 0xbfb8aa3b, v26
	v_exp_f32_e32 v17, v16
	v_mul_f32_e32 v16, 0xbfb8aa3b, v29
	v_exp_f32_e32 v20, v16
	v_cvt_pk_bf16_f32 v16, v18, v19
	v_add_f32_e32 v17, 1.0, v17
	v_rcp_f32_e32 v18, v17
	v_add_f32_e32 v17, 1.0, v20
	v_rcp_f32_e32 v19, v17
	v_and_b32_e32 v27, 0xffff0000, v21
	v_lshlrev_b32_e32 v28, 16, v21
	v_pk_mul_f32 v[20:21], v[28:29], v[26:27]
	s_waitcnt vmcnt(2)
	v_and_b32_e32 v27, 0xffff0000, v8
	v_pk_mul_f32 v[18:19], v[18:19], v[20:21]
	v_lshlrev_b32_e32 v20, 16, v8
	v_mul_f32_e32 v8, 0xbfb8aa3b, v20
	v_exp_f32_e32 v8, v8
	v_mul_f32_e32 v21, 0xbfb8aa3b, v27
	v_exp_f32_e32 v21, v21
	v_cvt_pk_bf16_f32 v17, v18, v19
	v_lshl_add_u64 v[18:19], v[12:13], 0, v[204:205]
	v_add_f32_e32 v8, 1.0, v8
	global_store_dwordx4 v[18:19], v[14:17], off
	s_waitcnt lgkmcnt(0)
	v_lshlrev_b32_e32 v26, 16, v22
	v_and_b32_e32 v19, 0xffff0000, v9
	v_rcp_f32_e32 v14, v8
	v_add_f32_e32 v8, 1.0, v21
	v_rcp_f32_e32 v15, v8
	v_and_b32_e32 v21, 0xffff0000, v22
	v_pk_mul_f32 v[16:17], v[26:27], v[20:21]
	v_lshlrev_b32_e32 v18, 16, v23
	v_pk_mul_f32 v[14:15], v[14:15], v[16:17]
	v_lshlrev_b32_e32 v16, 16, v9
	v_mul_f32_e32 v8, 0xbfb8aa3b, v16
	v_exp_f32_e32 v9, v8
	v_mul_f32_e32 v8, 0xbfb8aa3b, v19
	v_exp_f32_e32 v17, v8
	v_cvt_pk_bf16_f32 v8, v14, v15
	v_add_f32_e32 v9, 1.0, v9
	v_rcp_f32_e32 v14, v9
	v_add_f32_e32 v9, 1.0, v17
	v_rcp_f32_e32 v15, v9
	v_and_b32_e32 v17, 0xffff0000, v23
	v_pk_mul_f32 v[16:17], v[18:19], v[16:17]
	v_and_b32_e32 v19, 0xffff0000, v10
	v_pk_mul_f32 v[14:15], v[14:15], v[16:17]
	v_lshlrev_b32_e32 v16, 16, v10
	v_mul_f32_e32 v9, 0xbfb8aa3b, v16
	v_exp_f32_e32 v10, v9
	v_mul_f32_e32 v9, 0xbfb8aa3b, v19
	v_exp_f32_e32 v17, v9
	v_cvt_pk_bf16_f32 v9, v14, v15
	v_add_f32_e32 v10, 1.0, v10
	v_rcp_f32_e32 v14, v10
	v_add_f32_e32 v10, 1.0, v17
	v_rcp_f32_e32 v15, v10
	v_and_b32_e32 v17, 0xffff0000, v24
	v_lshlrev_b32_e32 v18, 16, v24
	v_pk_mul_f32 v[16:17], v[18:19], v[16:17]
	v_and_b32_e32 v19, 0xffff0000, v11
	v_pk_mul_f32 v[14:15], v[14:15], v[16:17]
	v_lshlrev_b32_e32 v16, 16, v11
	v_mul_f32_e32 v10, 0xbfb8aa3b, v16
	v_exp_f32_e32 v11, v10
	v_mul_f32_e32 v10, 0xbfb8aa3b, v19
	v_exp_f32_e32 v17, v10
	v_cvt_pk_bf16_f32 v10, v14, v15
	v_add_f32_e32 v11, 1.0, v11
	v_rcp_f32_e32 v14, v11
	v_add_f32_e32 v11, 1.0, v17
	v_rcp_f32_e32 v15, v11
	v_and_b32_e32 v17, 0xffff0000, v25
	v_lshlrev_b32_e32 v18, 16, v25
	v_pk_mul_f32 v[16:17], v[18:19], v[16:17]
	v_lshlrev_b32_e32 v204, 11, v35
	v_pk_mul_f32 v[14:15], v[14:15], v[16:17]
	s_waitcnt vmcnt(2)
; __device__ __forceinline__ unsigned cvtpk_s(float lo,float hi){f32x2_t v={lo,hi};bf16x2_t b=__builtin_convertvector(v,bf16x2_t);return __builtin_bit_cast(unsigned,b);}
; template<int THRL> __device__ __forceinline__ void attn_unit(int b,int h,int qb,int t0,float cqv,float mfix,const float*__restrict__ cf,float cref,unsigned*counter,const bf16*Q,const bf16*__restrict__ K,const bf16*__restrict__ V,bf16*O,const bf16*__restrict__ G,char*shm){
;     ...
;     for(int i=0;i<4;++i){const int row=i*8+(lane>>3),ch=lane&7; const u32x4 v=*(const u32x4*)(stg+row*64+ch*8); const u32x4 gv=gv4[i]; u32x4 w;
;       #pragma unroll
;       for(int c=0;c<4;++c){ const float ol=__uint_as_float(v[c]<<16), oh=__uint_as_float(v[c]&0xffff0000u), gl=__uint_as_float(gv[c]<<16), gh=__uint_as_float(gv[c]&0xffff0000u);
;         const float rl=ol*gl*__builtin_amdgcn_rcpf(1.f+__expf(-gl)), rh=oh*gh*__builtin_amdgcn_rcpf(1.f+__expf(-gh)); w[c]=cvtpk_s(rl,rh); }
;       ATTN_STORE16(Ow+(long)row*DM+ch*8,w);} }
;   if(tid==0) *(volatile __attribute__((address_space(3))) int*)((__attribute__((address_space(3))) char*)shm+LDS_MISC)=unext_;
;   asm volatile("s_waitcnt lgkmcnt(0)\n\ts_barrier":::"memory");
	v_lshlrev_b32_e32 v18, 16, v4
	v_cvt_pk_bf16_f32 v11, v14, v15
	v_lshl_add_u64 v[14:15], v[12:13], 0, v[204:205]
	v_and_b32_e32 v21, 0xffff0000, v4
	v_mul_f32_e32 v4, 0xbfb8aa3b, v18
	global_store_dwordx4 v[14:15], v[8:11], off
	v_exp_f32_e32 v4, v4
	v_or_b32_e32 v24, 16, v32
	v_mul_f32_e32 v9, 0xbfb8aa3b, v21
	v_exp_f32_e32 v14, v9
	v_lshl_add_u32 v8, v24, 7, v34
	ds_read_b128 v[8:11], v8 offset:51200
	v_add_f32_e32 v4, 1.0, v4
	v_rcp_f32_e32 v22, v4
	v_add_f32_e32 v4, 1.0, v14
	v_rcp_f32_e32 v23, v4
	v_or_b32_e32 v25, 24, v32
	v_lshl_add_u32 v4, v25, 7, v34
	ds_read_b128 v[14:17], v4 offset:51200
	s_waitcnt lgkmcnt(1)
	v_and_b32_e32 v19, 0xffff0000, v8
	v_lshlrev_b32_e32 v20, 16, v8
	v_pk_mul_f32 v[18:19], v[20:21], v[18:19]
	v_lshlrev_b32_e32 v20, 16, v5
	v_pk_mul_f32 v[18:19], v[22:23], v[18:19]
	v_and_b32_e32 v23, 0xffff0000, v5
	v_mul_f32_e32 v4, 0xbfb8aa3b, v20
	v_exp_f32_e32 v5, v4
	v_mul_f32_e32 v4, 0xbfb8aa3b, v23
	v_exp_f32_e32 v8, v4
	v_cvt_pk_bf16_f32 v4, v18, v19
	v_add_f32_e32 v5, 1.0, v5
	v_rcp_f32_e32 v18, v5
	v_add_f32_e32 v5, 1.0, v8
	v_rcp_f32_e32 v19, v5
	v_and_b32_e32 v21, 0xffff0000, v9
	v_lshlrev_b32_e32 v22, 16, v9
	v_pk_mul_f32 v[8:9], v[22:23], v[20:21]
	v_and_b32_e32 v21, 0xffff0000, v6
	v_pk_mul_f32 v[8:9], v[18:19], v[8:9]
	v_lshlrev_b32_e32 v18, 16, v6
	v_mul_f32_e32 v5, 0xbfb8aa3b, v18
	v_exp_f32_e32 v6, v5
	v_mul_f32_e32 v5, 0xbfb8aa3b, v21
	v_exp_f32_e32 v19, v5
	v_cvt_pk_bf16_f32 v5, v8, v9
	v_add_f32_e32 v6, 1.0, v6
	v_rcp_f32_e32 v8, v6
	v_add_f32_e32 v6, 1.0, v19
	v_rcp_f32_e32 v9, v6
	v_and_b32_e32 v19, 0xffff0000, v10
	v_lshlrev_b32_e32 v20, 16, v10
	v_pk_mul_f32 v[18:19], v[20:21], v[18:19]
	v_and_b32_e32 v21, 0xffff0000, v7
	v_pk_mul_f32 v[8:9], v[8:9], v[18:19]
	v_lshlrev_b32_e32 v18, 16, v7
	v_mul_f32_e32 v6, 0xbfb8aa3b, v18
	v_exp_f32_e32 v7, v6
	v_mul_f32_e32 v6, 0xbfb8aa3b, v21
	v_exp_f32_e32 v10, v6
	v_cvt_pk_bf16_f32 v6, v8, v9
	v_add_f32_e32 v7, 1.0, v7
	v_rcp_f32_e32 v8, v7
	v_add_f32_e32 v7, 1.0, v10
	v_rcp_f32_e32 v9, v7
	v_and_b32_e32 v19, 0xffff0000, v11
	v_lshlrev_b32_e32 v20, 16, v11
	v_pk_mul_f32 v[10:11], v[20:21], v[18:19]
	s_waitcnt vmcnt(2)
	v_and_b32_e32 v19, 0xffff0000, v0
	v_pk_mul_f32 v[8:9], v[8:9], v[10:11]
	v_lshlrev_b32_e32 v10, 16, v0
	v_mul_f32_e32 v0, 0xbfb8aa3b, v10
	v_exp_f32_e32 v0, v0
	v_mul_f32_e32 v11, 0xbfb8aa3b, v19
	v_exp_f32_e32 v11, v11
	v_lshlrev_b32_e32 v204, 11, v24
	v_cvt_pk_bf16_f32 v7, v8, v9
	v_lshl_add_u64 v[8:9], v[12:13], 0, v[204:205]
	v_add_f32_e32 v0, 1.0, v0
	global_store_dwordx4 v[8:9], v[4:7], off
	s_waitcnt lgkmcnt(0)
	v_lshlrev_b32_e32 v18, 16, v14
	v_and_b32_e32 v9, 0xffff0000, v1
	v_rcp_f32_e32 v4, v0
	v_add_f32_e32 v0, 1.0, v11
	v_rcp_f32_e32 v5, v0
	v_and_b32_e32 v11, 0xffff0000, v14
	v_pk_mul_f32 v[6:7], v[18:19], v[10:11]
	v_lshlrev_b32_e32 v8, 16, v15
	v_pk_mul_f32 v[4:5], v[4:5], v[6:7]
	v_lshlrev_b32_e32 v6, 16, v1
	v_mul_f32_e32 v0, 0xbfb8aa3b, v6
	v_exp_f32_e32 v1, v0
	v_mul_f32_e32 v0, 0xbfb8aa3b, v9
	v_exp_f32_e32 v7, v0
	v_cvt_pk_bf16_f32 v0, v4, v5
	v_add_f32_e32 v1, 1.0, v1
	v_rcp_f32_e32 v4, v1
	v_add_f32_e32 v1, 1.0, v7
	v_rcp_f32_e32 v5, v1
	v_and_b32_e32 v7, 0xffff0000, v15
	v_pk_mul_f32 v[6:7], v[8:9], v[6:7]
	v_and_b32_e32 v9, 0xffff0000, v2
	v_pk_mul_f32 v[4:5], v[4:5], v[6:7]
	v_lshlrev_b32_e32 v6, 16, v2
	v_mul_f32_e32 v1, 0xbfb8aa3b, v6
	v_exp_f32_e32 v2, v1
	v_mul_f32_e32 v1, 0xbfb8aa3b, v9
	v_exp_f32_e32 v7, v1
	v_cvt_pk_bf16_f32 v1, v4, v5
	v_add_f32_e32 v2, 1.0, v2
	v_rcp_f32_e32 v4, v2
	v_add_f32_e32 v2, 1.0, v7
	v_rcp_f32_e32 v5, v2
	v_and_b32_e32 v7, 0xffff0000, v16
	v_lshlrev_b32_e32 v8, 16, v16
	v_pk_mul_f32 v[6:7], v[8:9], v[6:7]
	v_and_b32_e32 v9, 0xffff0000, v3
	v_pk_mul_f32 v[4:5], v[4:5], v[6:7]
	v_lshlrev_b32_e32 v6, 16, v3
	v_mul_f32_e32 v2, 0xbfb8aa3b, v6
	v_exp_f32_e32 v3, v2
	v_mul_f32_e32 v2, 0xbfb8aa3b, v9
	v_exp_f32_e32 v7, v2
	v_cvt_pk_bf16_f32 v2, v4, v5
	v_add_f32_e32 v3, 1.0, v3
	v_rcp_f32_e32 v4, v3
	v_add_f32_e32 v3, 1.0, v7
	v_rcp_f32_e32 v5, v3
	v_and_b32_e32 v7, 0xffff0000, v17
	v_lshlrev_b32_e32 v8, 16, v17
	v_pk_mul_f32 v[6:7], v[8:9], v[6:7]
	v_lshlrev_b32_e32 v204, 11, v25
	v_pk_mul_f32 v[4:5], v[4:5], v[6:7]
	s_nop 0
	v_cvt_pk_bf16_f32 v3, v4, v5
	v_lshl_add_u64 v[4:5], v[12:13], 0, v[204:205]
	global_store_dwordx4 v[4:5], v[0:3], off
	s_and_saveexec_b64 s[4:5], vcc
	s_cbranch_execz .LBB0_844
	v_mov_b32_e32 v0, s60
	ds_write_b32 v0, v252
	s_branch .LBB0_844
